# MLA attention tile loop hand-rewritten (one barrier per tile, 3-slot LDS ring, pipelined K-fragment LDS reads, in-place P conversion) + deferred-max rescale: O/l rescaled only when a row max grows by
# speedup vs baseline: 1.0122x; 1.0122x over previous
.LBB0_429:
	s_xor_b64 s[10:11], s[4:5], -1
	s_and_b64 s[2:3], s[4:5], exec
	s_cselect_b32 s2, s15, s14
	s_lshl_b32 s2, s2, 8
	s_add_i32 s18, s2, s13
	v_or_b32_e32 v224, s18, v185
	v_ashrrev_i32_e32 v225, 31, v224
	v_lshl_add_u64 v[222:223], s[0:1], 0, v[224:225]
	s_movk_i32 s3, 0x1800
	v_mad_u64_u32 v[6:7], s[4:5], v222, s3, v[202:203]
	v_lshlrev_b64 v[14:15], 8, v[224:225]
	v_mad_i32_i24 v7, v223, s3, v7
	v_lshl_add_u64 v[14:15], v[174:175], 0, v[14:15]
	global_load_dwordx4 v[148:151], v[6:7], off
	global_load_dwordx4 v[144:147], v[6:7], off offset:32
	global_load_dwordx4 v[140:143], v[6:7], off offset:64
	global_load_dwordx4 v[132:135], v[6:7], off offset:96
	global_load_dwordx4 v[124:127], v[6:7], off offset:128
	global_load_dwordx4 v[120:123], v[6:7], off offset:160
	global_load_dwordx4 v[116:119], v[6:7], off offset:192
	global_load_dwordx4 v[112:115], v[6:7], off offset:224
	global_load_dwordx4 v[10:13], v[6:7], off offset:256
	global_load_dwordx4 v[2:5], v[6:7], off offset:288
	global_load_dwordx4 v[48:51], v[6:7], off offset:320
	s_nop 0
	global_load_dwordx4 v[6:9], v[6:7], off offset:352
	s_nop 0
	global_load_dwordx4 v[52:55], v[14:15], off offset:48
	global_load_dwordx4 v[56:59], v[14:15], off offset:32
	global_load_dwordx4 v[60:63], v[14:15], off offset:16
	global_load_dwordx4 v[64:67], v[14:15], off
	v_add_u32_e32 v1, v190, v242
	s_or_b32 s16, s18, 31
	s_or_b32 s3, s2, 0xc0
	s_mov_b32 s19, 0
	v_mov_b32_e32 v249, 0xf149f2ca
	v_mov_b32_e32 v225, 0
	v_mov_b64_e32 v[226:227], v[220:221]
	v_mov_b64_e32 v[228:229], v[218:219]
	v_mov_b64_e32 v[230:231], v[216:217]
	s_mov_b32 s24, 0
	s_waitcnt vmcnt(0)
	v_and_b32_e32 v69, 0xffff0000, v10
	v_lshlrev_b32_e32 v68, 16, v10
	v_and_b32_e32 v71, 0xffff0000, v48
	v_lshlrev_b32_e32 v70, 16, v48
	v_mov_b32_e32 v73, v66
	v_mov_b32_e32 v66, v65
	v_mov_b32_e32 v72, v64
	v_pk_mul_f32 v[64:65], v[66:67], v[70:71]
	v_lshlrev_b32_e32 v10, 16, v49
	v_pk_fma_f32 v[64:65], v[72:73], v[68:69], v[64:65] neg_lo:[0,0,1] neg_hi:[0,0,1]
	v_mov_b32_e32 v48, v60
	v_cvt_pk_bf16_f32 v136, v64, v65
	v_pk_mul_f32 v[64:65], v[72:73], v[70:71]
	s_nop 0
	v_pk_fma_f32 v[64:65], v[66:67], v[68:69], v[64:65]
	s_nop 0
	v_cvt_pk_bf16_f32 v128, v64, v65
	v_and_b32_e32 v65, 0xffff0000, v11
	v_lshlrev_b32_e32 v64, 16, v11
	v_and_b32_e32 v11, 0xffff0000, v49
	v_mov_b32_e32 v49, v62
	v_mov_b32_e32 v62, v61
	v_pk_mul_f32 v[60:61], v[62:63], v[10:11]
	v_pk_mul_f32 v[10:11], v[48:49], v[10:11]
	v_pk_fma_f32 v[60:61], v[48:49], v[64:65], v[60:61] neg_lo:[0,0,1] neg_hi:[0,0,1]
	v_pk_fma_f32 v[10:11], v[62:63], v[64:65], v[10:11]
	v_cvt_pk_bf16_f32 v137, v60, v61
	v_and_b32_e32 v49, 0xffff0000, v50
	v_lshlrev_b32_e32 v48, 16, v50
	v_mov_b32_e32 v60, v56
	v_mov_b32_e32 v61, v58
	v_mov_b32_e32 v58, v57
	v_cvt_pk_bf16_f32 v129, v10, v11
	v_and_b32_e32 v11, 0xffff0000, v12
	v_lshlrev_b32_e32 v10, 16, v12
	v_pk_mul_f32 v[56:57], v[58:59], v[48:49]
	v_pk_mul_f32 v[48:49], v[60:61], v[48:49]
	v_pk_fma_f32 v[56:57], v[60:61], v[10:11], v[56:57] neg_lo:[0,0,1] neg_hi:[0,0,1]
	v_pk_fma_f32 v[10:11], v[58:59], v[10:11], v[48:49]
	v_lshlrev_b32_e32 v12, 16, v51
	v_cvt_pk_bf16_f32 v130, v10, v11
	v_and_b32_e32 v11, 0xffff0000, v13
	v_lshlrev_b32_e32 v10, 16, v13
	v_and_b32_e32 v13, 0xffff0000, v51
	v_mov_b32_e32 v48, v52
	v_mov_b32_e32 v49, v54
	v_mov_b32_e32 v54, v53
	v_pk_mul_f32 v[50:51], v[54:55], v[12:13]
	v_pk_mul_f32 v[12:13], v[48:49], v[12:13]
	v_pk_fma_f32 v[50:51], v[48:49], v[10:11], v[50:51] neg_lo:[0,0,1] neg_hi:[0,0,1]
	v_pk_fma_f32 v[10:11], v[54:55], v[10:11], v[12:13]
	v_cvt_pk_bf16_f32 v138, v56, v57
	v_cvt_pk_bf16_f32 v139, v50, v51
	v_cvt_pk_bf16_f32 v131, v10, v11
	global_load_dwordx4 v[10:13], v[14:15], off offset:176
	global_load_dwordx4 v[48:51], v[14:15], off offset:160
	global_load_dwordx4 v[52:55], v[14:15], off offset:144
	global_load_dwordx4 v[56:59], v[14:15], off offset:128
	v_and_b32_e32 v61, 0xffff0000, v6
	v_lshlrev_b32_e32 v60, 16, v6
	v_and_b32_e32 v15, 0xffff0000, v2
	v_lshlrev_b32_e32 v14, 16, v2
	v_lshlrev_b32_e32 v2, 16, v7
	s_waitcnt vmcnt(0)
	v_mov_b32_e32 v6, v52
	v_mov_b32_e32 v63, v58
	v_mov_b32_e32 v58, v57
	v_mov_b32_e32 v62, v56
	v_pk_mul_f32 v[56:57], v[58:59], v[60:61]
	s_nop 0
	v_pk_fma_f32 v[56:57], v[62:63], v[14:15], v[56:57] neg_lo:[0,0,1] neg_hi:[0,0,1]
	s_nop 0
	v_cvt_pk_bf16_f32 v156, v56, v57
	v_pk_mul_f32 v[56:57], v[62:63], v[60:61]
	s_nop 0
	v_pk_fma_f32 v[14:15], v[58:59], v[14:15], v[56:57]
	s_nop 0
	v_cvt_pk_bf16_f32 v152, v14, v15
	v_and_b32_e32 v15, 0xffff0000, v3
	v_lshlrev_b32_e32 v14, 16, v3
	v_and_b32_e32 v3, 0xffff0000, v7
	v_mov_b32_e32 v7, v54
	v_mov_b32_e32 v54, v53
	v_pk_mul_f32 v[52:53], v[54:55], v[2:3]
	v_pk_mul_f32 v[2:3], v[6:7], v[2:3]
	v_pk_fma_f32 v[52:53], v[6:7], v[14:15], v[52:53] neg_lo:[0,0,1] neg_hi:[0,0,1]
	v_pk_fma_f32 v[2:3], v[54:55], v[14:15], v[2:3]
	v_and_b32_e32 v7, 0xffff0000, v8
	v_lshlrev_b32_e32 v6, 16, v8
	v_mov_b32_e32 v14, v48
	v_mov_b32_e32 v15, v50
	v_mov_b32_e32 v50, v49
	v_cvt_pk_bf16_f32 v153, v2, v3
	v_and_b32_e32 v3, 0xffff0000, v4
	v_lshlrev_b32_e32 v2, 16, v4
	v_pk_mul_f32 v[48:49], v[50:51], v[6:7]
	v_pk_mul_f32 v[6:7], v[14:15], v[6:7]
	v_pk_fma_f32 v[48:49], v[14:15], v[2:3], v[48:49] neg_lo:[0,0,1] neg_hi:[0,0,1]
	v_pk_fma_f32 v[2:3], v[50:51], v[2:3], v[6:7]
	v_lshlrev_b32_e32 v4, 16, v9
	v_cvt_pk_bf16_f32 v154, v2, v3
	v_and_b32_e32 v3, 0xffff0000, v5
	v_lshlrev_b32_e32 v2, 16, v5
	v_and_b32_e32 v5, 0xffff0000, v9
	v_mov_b32_e32 v6, v10
	v_mov_b32_e32 v7, v12
	v_mov_b32_e32 v12, v11
	v_pk_mul_f32 v[8:9], v[12:13], v[4:5]
	v_pk_mul_f32 v[4:5], v[6:7], v[4:5]
	v_pk_fma_f32 v[8:9], v[6:7], v[2:3], v[8:9] neg_lo:[0,0,1] neg_hi:[0,0,1]
	v_pk_fma_f32 v[2:3], v[12:13], v[2:3], v[4:5]
	v_cvt_pk_bf16_f32 v157, v52, v53
	v_cvt_pk_bf16_f32 v158, v48, v49
	v_cvt_pk_bf16_f32 v159, v8, v9
	v_cvt_pk_bf16_f32 v155, v2, v3
	global_load_dwordx4 v[2:5], v[204:205], off
	global_load_dwordx4 v[6:9], v[206:207], off
	global_load_dwordx4 v[52:55], v[208:209], off
	global_load_dwordx4 v[48:51], v[210:211], off
	global_load_dwordx4 v[10:13], v[212:213], off
	s_waitcnt vmcnt(0)
	ds_write_b128 v247, v[2:5]
	ds_write_b128 v247, v[6:9] offset:12800
	ds_write_b128 v1, v[52:55] offset:256
	v_add_u32_e32 v1, 0x6400, v248
	ds_write2_b64 v1, v[48:49], v[50:51] offset1:1
	v_add_u32_e32 v1, 0x8600, v248
	v_mov_b32_e32 v14, v0
	v_mov_b32_e32 v15, v0
	ds_write2_b64 v1, v[10:11], v[12:13] offset1:1
	s_mov_b64 s[4:5], 0x40000
	v_lshl_add_u64 v[2:3], v[204:205], 0, s[4:5]
	v_lshl_add_u64 v[4:5], v[206:207], 0, s[4:5]
	s_mov_b64 s[4:5], 0x2000
	v_lshl_add_u64 v[6:7], v[208:209], 0, s[4:5]
	global_load_dwordx4 v[56:59], v[2:3], off
	global_load_dwordx4 v[60:63], v[4:5], off
	global_load_dwordx4 v[64:67], v[6:7], off
	global_load_dwordx4 v[68:71], v[210:211], off offset:128
	global_load_dwordx4 v[72:75], v[212:213], off offset:128
	s_waitcnt vmcnt(0)
	ds_write_b128 v247, v[56:59] offset:43008
	ds_write_b128 v247, v[60:63] offset:55808
	v_add_u32_e32 v1, v190, v242
	ds_write_b128 v1, v[64:67] offset:43264
	v_add_u32_e32 v1, 0x10c00, v248
	ds_write2_b64 v1, v[68:69], v[70:71] offset1:1
	v_add_u32_e32 v1, 0x12e00, v248
	ds_write2_b64 v1, v[72:73], v[74:75] offset1:1
	v_mov_b32_e32 v1, v0
	v_mov_b32_e32 v2, v0
	v_mov_b32_e32 v3, v0
	v_mov_b32_e32 v4, v0
	v_mov_b32_e32 v5, v0
	v_mov_b32_e32 v6, v0
	v_mov_b32_e32 v7, v0
	v_mov_b32_e32 v8, v0
	v_mov_b32_e32 v9, v0
	v_mov_b32_e32 v10, v0
	v_mov_b32_e32 v11, v0
	v_mov_b32_e32 v12, v0
	v_mov_b32_e32 v13, v0
	v_mov_b64_e32 v[62:63], v[14:15]
	v_mov_b64_e32 v[78:79], v[14:15]
	v_mov_b64_e32 v[94:95], v[14:15]
	v_mov_b64_e32 v[110:111], v[14:15]
	v_mov_b64_e32 v[60:61], v[12:13]
	v_mov_b64_e32 v[58:59], v[10:11]
	v_mov_b64_e32 v[56:57], v[8:9]
	v_mov_b64_e32 v[54:55], v[6:7]
	v_mov_b64_e32 v[52:53], v[4:5]
	v_mov_b64_e32 v[50:51], v[2:3]
	v_mov_b64_e32 v[48:49], v[0:1]
	v_mov_b64_e32 v[76:77], v[12:13]
	v_mov_b64_e32 v[74:75], v[10:11]
	v_mov_b64_e32 v[72:73], v[8:9]
	v_mov_b64_e32 v[70:71], v[6:7]
	v_mov_b64_e32 v[68:69], v[4:5]
	v_mov_b64_e32 v[66:67], v[2:3]
	v_mov_b64_e32 v[64:65], v[0:1]
	v_mov_b64_e32 v[92:93], v[12:13]
	v_mov_b64_e32 v[90:91], v[10:11]
	v_mov_b64_e32 v[88:89], v[8:9]
	v_mov_b64_e32 v[86:87], v[6:7]
	v_mov_b64_e32 v[84:85], v[4:5]
	v_mov_b64_e32 v[82:83], v[2:3]
	v_mov_b64_e32 v[80:81], v[0:1]
	v_mov_b64_e32 v[108:109], v[12:13]
	v_mov_b64_e32 v[106:107], v[10:11]
	v_mov_b64_e32 v[104:105], v[8:9]
	v_mov_b64_e32 v[102:103], v[6:7]
	v_mov_b64_e32 v[100:101], v[4:5]
	v_mov_b64_e32 v[98:99], v[2:3]
	v_mov_b64_e32 v[96:97], v[0:1]
	s_branch .LBB0_432
.LBB0_432:
.Lm2_A_top:
	s_waitcnt lgkmcnt(0)
	s_barrier
	s_add_i32 s25, s24, 16
	s_cmp_gt_i32 s19, s16
	s_cbranch_scc1 .Lm2_h1done1
	v_add3_u32 v1, s25, v244, v170
	ds_read_b128 v[2:5], v1
	ds_read_b128 v[6:9], v1 offset:12800
	ds_read_b128 v[10:13], v1 offset:32
	ds_read_b128 v[160:163], v1 offset:12832
	ds_read_b128 v[164:167], v1 offset:64
	ds_read_b128 v[186:189], v1 offset:12864
	s_waitcnt lgkmcnt(5)
	v_mfma_f32_32x32x16_bf16 v[16:31], v[2:5], v[148:151], 0
	ds_read_b128 v[2:5], v1 offset:96
	s_waitcnt lgkmcnt(5)
	v_mfma_f32_32x32x16_bf16 v[32:47], v[6:9], v[148:151], 0
	ds_read_b128 v[6:9], v1 offset:12896
	s_waitcnt lgkmcnt(5)
	v_mfma_f32_32x32x16_bf16 v[16:31], v[10:13], v[144:147], v[16:31]
	ds_read_b128 v[10:13], v1 offset:128
	s_waitcnt lgkmcnt(5)
	v_mfma_f32_32x32x16_bf16 v[32:47], v[160:163], v[144:147], v[32:47]
	ds_read_b128 v[160:163], v1 offset:12928
	s_waitcnt lgkmcnt(5)
	v_mfma_f32_32x32x16_bf16 v[16:31], v[164:167], v[140:143], v[16:31]
	ds_read_b128 v[164:167], v1 offset:160
	s_waitcnt lgkmcnt(5)
	v_mfma_f32_32x32x16_bf16 v[32:47], v[186:189], v[140:143], v[32:47]
	ds_read_b128 v[186:189], v1 offset:12960
	s_waitcnt lgkmcnt(5)
	v_mfma_f32_32x32x16_bf16 v[16:31], v[2:5], v[132:135], v[16:31]
	ds_read_b128 v[2:5], v1 offset:192
	s_waitcnt lgkmcnt(5)
	v_mfma_f32_32x32x16_bf16 v[32:47], v[6:9], v[132:135], v[32:47]
	ds_read_b128 v[6:9], v1 offset:12992
	s_waitcnt lgkmcnt(5)
	v_mfma_f32_32x32x16_bf16 v[16:31], v[10:13], v[124:127], v[16:31]
	ds_read_b128 v[10:13], v1 offset:224
	s_waitcnt lgkmcnt(5)
	v_mfma_f32_32x32x16_bf16 v[32:47], v[160:163], v[124:127], v[32:47]
	ds_read_b128 v[160:163], v1 offset:13024
	s_waitcnt lgkmcnt(5)
	v_mfma_f32_32x32x16_bf16 v[16:31], v[164:167], v[120:123], v[16:31]
	ds_read_b128 v[164:167], v1 offset:256
	s_waitcnt lgkmcnt(5)
	v_mfma_f32_32x32x16_bf16 v[32:47], v[186:189], v[120:123], v[32:47]
	ds_read_b128 v[186:189], v1 offset:13056
	s_waitcnt lgkmcnt(5)
	v_mfma_f32_32x32x16_bf16 v[16:31], v[2:5], v[116:119], v[16:31]
	ds_read_b128 v[2:5], v1 offset:288
	s_waitcnt lgkmcnt(5)
	v_mfma_f32_32x32x16_bf16 v[32:47], v[6:9], v[116:119], v[32:47]
	ds_read_b128 v[6:9], v1 offset:13088
	s_waitcnt lgkmcnt(5)
	v_mfma_f32_32x32x16_bf16 v[16:31], v[10:13], v[112:115], v[16:31]
	ds_read_b128 v[10:13], v1 offset:320
	s_waitcnt lgkmcnt(5)
	v_mfma_f32_32x32x16_bf16 v[32:47], v[160:163], v[112:115], v[32:47]
	ds_read_b128 v[160:163], v1 offset:13120
	s_waitcnt lgkmcnt(5)
	v_mfma_f32_32x32x16_bf16 v[16:31], v[164:167], v[136:139], v[16:31]
	ds_read_b128 v[164:167], v1 offset:352
	s_waitcnt lgkmcnt(5)
	v_mfma_f32_32x32x16_bf16 v[32:47], v[186:189], v[136:139], v[32:47]
	ds_read_b128 v[186:189], v1 offset:13152
	s_waitcnt lgkmcnt(5)
	v_mfma_f32_32x32x16_bf16 v[16:31], v[2:5], v[156:159], v[16:31]
	s_waitcnt lgkmcnt(4)
	v_mfma_f32_32x32x16_bf16 v[32:47], v[6:9], v[156:159], v[32:47]
	s_waitcnt lgkmcnt(3)
	v_mfma_f32_32x32x16_bf16 v[16:31], v[10:13], v[128:131], v[16:31]
	s_waitcnt lgkmcnt(2)
	v_mfma_f32_32x32x16_bf16 v[32:47], v[160:163], v[128:131], v[32:47]
	s_waitcnt lgkmcnt(1)
	v_mfma_f32_32x32x16_bf16 v[16:31], v[164:167], v[152:155], v[16:31]
	s_waitcnt lgkmcnt(0)
	v_mfma_f32_32x32x16_bf16 v[32:47], v[186:189], v[152:155], v[32:47]
.Lm2_h1done1:
	s_nop 7
	s_cmp_eq_u32 s19, 0
	s_cbranch_scc1 .Lm2_A_noload
	v_lshl_add_u64 v[2:3], s[90:91], 0, v[226:227]
	s_mov_b32 s2, 0x1e140000
	v_add_co_u32_e32 v4, vcc, s2, v2
	s_mov_b32 s2, 0x1e160000
	s_nop 0
	v_addc_co_u32_e32 v5, vcc, 0, v3, vcc
	v_add_co_u32_e32 v6, vcc, s2, v2
	v_lshl_add_u64 v[14:15], s[90:91], 0, v[230:231]
	s_nop 0
	v_addc_co_u32_e32 v7, vcc, 0, v3, vcc
	s_mov_b32 s2, 0x20100000
	v_add_co_u32_e32 v160, vcc, s2, v14
	v_lshl_add_u64 v[10:11], s[90:91], 0, v[228:229]
	s_nop 0
	v_addc_co_u32_e32 v161, vcc, 0, v15, vcc
	v_add_co_u32_e32 v14, vcc, 0x20200000, v14
	s_nop 1
	v_addc_co_u32_e32 v15, vcc, 0, v15, vcc
	global_load_dwordx4 v[2:5], v[4:5], off
	s_nop 0
	global_load_dwordx4 v[6:9], v[6:7], off
	s_nop 0
	global_load_dwordx4 v[10:13], v[10:11], off
	s_nop 0
	global_load_dwordx4 v[160:163], v[160:161], off offset:128
	global_load_dwordx4 v[164:167], v[14:15], off offset:128
.Lm2_A_noload:
	s_add_i32 s25, s24, 16
	s_cmp_gt_i32 s19, s16
	s_cbranch_scc1 .Lm2_h2done2
	s_add_i32 s4, s19, 63
	s_cmp_lt_i32 s4, s18
	s_cbranch_scc1 .Lm2_nomask2
	v_add_u32_e32 v14, s19, v245
	v_sub_u32_e32 v14, v224, v14
	v_cmp_le_i32_e32 vcc, 0, v14
	s_nop 1
	v_cndmask_b32_e32 v16, v237, v16, vcc
	v_cmp_le_i32_e32 vcc, 1, v14
	s_nop 1
	v_cndmask_b32_e32 v17, v237, v17, vcc
	v_cmp_le_i32_e32 vcc, 2, v14
	s_nop 1
	v_cndmask_b32_e32 v18, v237, v18, vcc
	v_cmp_le_i32_e32 vcc, 3, v14
	s_nop 1
	v_cndmask_b32_e32 v19, v237, v19, vcc
	v_cmp_le_i32_e32 vcc, 8, v14
	s_nop 1
	v_cndmask_b32_e32 v20, v237, v20, vcc
	v_cmp_le_i32_e32 vcc, 9, v14
	s_nop 1
	v_cndmask_b32_e32 v21, v237, v21, vcc
	v_cmp_le_i32_e32 vcc, 10, v14
	s_nop 1
	v_cndmask_b32_e32 v22, v237, v22, vcc
	v_cmp_le_i32_e32 vcc, 11, v14
	s_nop 1
	v_cndmask_b32_e32 v23, v237, v23, vcc
	v_cmp_le_i32_e32 vcc, 16, v14
	s_nop 1
	v_cndmask_b32_e32 v24, v237, v24, vcc
	v_cmp_le_i32_e32 vcc, 17, v14
	s_nop 1
	v_cndmask_b32_e32 v25, v237, v25, vcc
	v_cmp_le_i32_e32 vcc, 18, v14
	s_nop 1
	v_cndmask_b32_e32 v26, v237, v26, vcc
	v_cmp_le_i32_e32 vcc, 19, v14
	s_nop 1
	v_cndmask_b32_e32 v27, v237, v27, vcc
	v_cmp_le_i32_e32 vcc, 24, v14
	s_nop 1
	v_cndmask_b32_e32 v28, v237, v28, vcc
	v_cmp_le_i32_e32 vcc, 25, v14
	s_nop 1
	v_cndmask_b32_e32 v29, v237, v29, vcc
	v_cmp_le_i32_e32 vcc, 26, v14
	s_nop 1
	v_cndmask_b32_e32 v30, v237, v30, vcc
	v_cmp_le_i32_e32 vcc, 27, v14
	s_nop 1
	v_cndmask_b32_e32 v31, v237, v31, vcc
	v_cmp_le_i32_e32 vcc, 32, v14
	s_nop 1
	v_cndmask_b32_e32 v32, v237, v32, vcc
	v_cmp_le_i32_e32 vcc, 33, v14
	s_nop 1
	v_cndmask_b32_e32 v33, v237, v33, vcc
	v_cmp_le_i32_e32 vcc, 34, v14
	s_nop 1
	v_cndmask_b32_e32 v34, v237, v34, vcc
	v_cmp_le_i32_e32 vcc, 35, v14
	s_nop 1
	v_cndmask_b32_e32 v35, v237, v35, vcc
	v_cmp_le_i32_e32 vcc, 40, v14
	s_nop 1
	v_cndmask_b32_e32 v36, v237, v36, vcc
	v_cmp_le_i32_e32 vcc, 41, v14
	s_nop 1
	v_cndmask_b32_e32 v37, v237, v37, vcc
	v_cmp_le_i32_e32 vcc, 42, v14
	s_nop 1
	v_cndmask_b32_e32 v38, v237, v38, vcc
	v_cmp_le_i32_e32 vcc, 43, v14
	s_nop 1
	v_cndmask_b32_e32 v39, v237, v39, vcc
	v_cmp_le_i32_e32 vcc, 48, v14
	s_nop 1
	v_cndmask_b32_e32 v40, v237, v40, vcc
	v_cmp_le_i32_e32 vcc, 49, v14
	s_nop 1
	v_cndmask_b32_e32 v41, v237, v41, vcc
	v_cmp_le_i32_e32 vcc, 50, v14
	s_nop 1
	v_cndmask_b32_e32 v42, v237, v42, vcc
	v_cmp_le_i32_e32 vcc, 51, v14
	s_nop 1
	v_cndmask_b32_e32 v43, v237, v43, vcc
	v_cmp_le_i32_e32 vcc, 56, v14
	s_nop 1
	v_cndmask_b32_e32 v44, v237, v44, vcc
	v_cmp_le_i32_e32 vcc, 57, v14
	s_nop 1
	v_cndmask_b32_e32 v45, v237, v45, vcc
	v_cmp_le_i32_e32 vcc, 58, v14
	s_nop 1
	v_cndmask_b32_e32 v46, v237, v46, vcc
	v_cmp_le_i32_e32 vcc, 59, v14
	s_nop 1
	v_cndmask_b32_e32 v47, v237, v47, vcc
.Lm2_nomask2:
	v_max3_f32 v1, v16, v17, s49
	v_max3_f32 v1, v1, v18, v19
	v_max3_f32 v1, v1, v20, v21
	v_max3_f32 v1, v1, v22, v23
	v_max3_f32 v1, v1, v24, v25
	v_max3_f32 v1, v1, v26, v27
	v_max3_f32 v1, v1, v28, v29
	v_max3_f32 v1, v1, v30, v31
	v_max3_f32 v1, v1, v32, v33
	v_max3_f32 v1, v1, v34, v35
	v_max3_f32 v1, v1, v36, v37
	v_max3_f32 v1, v1, v38, v39
	v_max3_f32 v1, v1, v40, v41
	v_max3_f32 v1, v1, v42, v43
	v_max3_f32 v1, v1, v44, v45
	v_max3_f32 v1, v1, v46, v47
	ds_bpermute_b32 v15, v246, v1
	s_waitcnt lgkmcnt(0)
	v_max_f32_e32 v1, v1, v15
	v_mul_f32_e32 v1, 0x3dd53b94, v1
	v_sub_f32_e32 v15, v1, v249
	v_cmp_lt_f32_e32 vcc, 8.0, v15
	s_cbranch_vccz .Lm2_lazy2
	v_max_f32_e32 v1, v249, v1
	v_sub_f32_e32 v14, v249, v1
	v_exp_f32_e32 v14, v14
	v_mov_b32_e32 v249, v1
	v_fma_f32 v16, v16, s50, -v1
	v_exp_f32_e32 v16, v16
	v_fma_f32 v17, v17, s50, -v1
	v_exp_f32_e32 v17, v17
	v_fma_f32 v18, v18, s50, -v1
	v_exp_f32_e32 v18, v18
	v_fma_f32 v19, v19, s50, -v1
	v_exp_f32_e32 v19, v19
	v_fma_f32 v20, v20, s50, -v1
	v_exp_f32_e32 v20, v20
	v_fma_f32 v21, v21, s50, -v1
	v_exp_f32_e32 v21, v21
	v_fma_f32 v22, v22, s50, -v1
	v_exp_f32_e32 v22, v22
	v_fma_f32 v23, v23, s50, -v1
	v_exp_f32_e32 v23, v23
	v_fma_f32 v24, v24, s50, -v1
	v_exp_f32_e32 v24, v24
	v_fma_f32 v25, v25, s50, -v1
	v_exp_f32_e32 v25, v25
	v_fma_f32 v26, v26, s50, -v1
	v_exp_f32_e32 v26, v26
	v_fma_f32 v27, v27, s50, -v1
	v_exp_f32_e32 v27, v27
	v_fma_f32 v28, v28, s50, -v1
	v_exp_f32_e32 v28, v28
	v_fma_f32 v29, v29, s50, -v1
	v_exp_f32_e32 v29, v29
	v_fma_f32 v30, v30, s50, -v1
	v_exp_f32_e32 v30, v30
	v_fma_f32 v31, v31, s50, -v1
	v_exp_f32_e32 v31, v31
	v_fma_f32 v32, v32, s50, -v1
	v_exp_f32_e32 v32, v32
	v_fma_f32 v33, v33, s50, -v1
	v_exp_f32_e32 v33, v33
	v_fma_f32 v34, v34, s50, -v1
	v_exp_f32_e32 v34, v34
	v_fma_f32 v35, v35, s50, -v1
	v_exp_f32_e32 v35, v35
	v_fma_f32 v36, v36, s50, -v1
	v_exp_f32_e32 v36, v36
	v_fma_f32 v37, v37, s50, -v1
	v_exp_f32_e32 v37, v37
	v_fma_f32 v38, v38, s50, -v1
	v_exp_f32_e32 v38, v38
	v_fma_f32 v39, v39, s50, -v1
	v_exp_f32_e32 v39, v39
	v_fma_f32 v40, v40, s50, -v1
	v_exp_f32_e32 v40, v40
	v_fma_f32 v41, v41, s50, -v1
	v_exp_f32_e32 v41, v41
	v_fma_f32 v42, v42, s50, -v1
	v_exp_f32_e32 v42, v42
	v_fma_f32 v43, v43, s50, -v1
	v_exp_f32_e32 v43, v43
	v_fma_f32 v44, v44, s50, -v1
	v_exp_f32_e32 v44, v44
	v_fma_f32 v45, v45, s50, -v1
	v_exp_f32_e32 v45, v45
	v_fma_f32 v46, v46, s50, -v1
	v_exp_f32_e32 v46, v46
	v_fma_f32 v47, v47, s50, -v1
	v_exp_f32_e32 v47, v47
	v_pk_mul_f32 v[96:97], v[96:97], v[14:15] op_sel_hi:[1,0]
	v_pk_mul_f32 v[98:99], v[98:99], v[14:15] op_sel_hi:[1,0]
	v_pk_mul_f32 v[100:101], v[100:101], v[14:15] op_sel_hi:[1,0]
	v_pk_mul_f32 v[102:103], v[102:103], v[14:15] op_sel_hi:[1,0]
	v_pk_mul_f32 v[104:105], v[104:105], v[14:15] op_sel_hi:[1,0]
	v_pk_mul_f32 v[106:107], v[106:107], v[14:15] op_sel_hi:[1,0]
	v_pk_mul_f32 v[108:109], v[108:109], v[14:15] op_sel_hi:[1,0]
	v_pk_mul_f32 v[110:111], v[110:111], v[14:15] op_sel_hi:[1,0]
	v_add_f32_e32 v1, v16, v17
	v_add_f32_e32 v15, v24, v25
	v_add_f32_e32 v238, v32, v33
	v_add_f32_e32 v186, v40, v41
	v_add_f32_e32 v1, v18, v1
	v_add_f32_e32 v15, v26, v15
	v_add_f32_e32 v238, v34, v238
	v_add_f32_e32 v186, v42, v186
	v_add_f32_e32 v1, v19, v1
	v_add_f32_e32 v15, v27, v15
	v_add_f32_e32 v238, v35, v238
	v_add_f32_e32 v186, v43, v186
	v_add_f32_e32 v1, v20, v1
	v_add_f32_e32 v15, v28, v15
	v_add_f32_e32 v238, v36, v238
	v_add_f32_e32 v186, v44, v186
	v_add_f32_e32 v1, v21, v1
	v_add_f32_e32 v15, v29, v15
	v_add_f32_e32 v238, v37, v238
	v_add_f32_e32 v186, v45, v186
	v_add_f32_e32 v1, v22, v1
	v_add_f32_e32 v15, v30, v15
	v_add_f32_e32 v238, v38, v238
	v_add_f32_e32 v186, v46, v186
	v_add_f32_e32 v1, v23, v1
	v_add_f32_e32 v15, v31, v15
	v_add_f32_e32 v238, v39, v238
	v_add_f32_e32 v186, v47, v186
	v_add_f32_e32 v1, v1, v15
	v_add_f32_e32 v238, v238, v186
	v_add_f32_e32 v1, v1, v238
	v_fmac_f32_e32 v1, v225, v14
	v_mov_b32_e32 v225, v1
	v_add3_u32 v186, s25, v168, v169
	v_add_u32_e32 v187, 0x7000, v186
	v_add_u32_e32 v188, 0x8000, v186
	v_add_u32_e32 v189, 0x9000, v186
	v_add_u32_e32 v186, 0x6000, v186
	v_cvt_pk_bf16_f32 v16, v16, v17
	v_cvt_pk_bf16_f32 v17, v18, v19
	v_cvt_pk_bf16_f32 v18, v20, v21
	v_cvt_pk_bf16_f32 v19, v22, v23
	v_cvt_pk_bf16_f32 v20, v24, v25
	v_cvt_pk_bf16_f32 v21, v26, v27
	v_cvt_pk_bf16_f32 v22, v28, v29
	v_cvt_pk_bf16_f32 v23, v30, v31
	v_cvt_pk_bf16_f32 v24, v32, v33
	v_cvt_pk_bf16_f32 v25, v34, v35
	v_cvt_pk_bf16_f32 v26, v36, v37
	v_cvt_pk_bf16_f32 v27, v38, v39
	v_cvt_pk_bf16_f32 v28, v40, v41
	v_cvt_pk_bf16_f32 v29, v42, v43
	v_cvt_pk_bf16_f32 v30, v44, v45
	v_cvt_pk_bf16_f32 v31, v46, v47
	ds_read2_b64 v[32:35], v186 offset0:128 offset1:130
	ds_read2_b64 v[36:39], v186 offset0:132 offset1:134
	ds_read2_b64 v[40:43], v186 offset0:136 offset1:138
	ds_read2_b64 v[44:47], v186 offset0:140 offset1:142
	s_waitcnt lgkmcnt(3)
	v_mfma_f32_32x32x16_bf16 v[96:111], v[32:35], v[16:19], v[96:111]
	v_pk_mul_f32 v[80:81], v[80:81], v[14:15] op_sel_hi:[1,0]
	v_pk_mul_f32 v[82:83], v[82:83], v[14:15] op_sel_hi:[1,0]
	ds_read2_b64 v[32:35], v187 offset0:160 offset1:162
	s_waitcnt lgkmcnt(3)
	v_mfma_f32_32x32x16_bf16 v[96:111], v[36:39], v[20:23], v[96:111]
	v_pk_mul_f32 v[84:85], v[84:85], v[14:15] op_sel_hi:[1,0]
	v_pk_mul_f32 v[86:87], v[86:87], v[14:15] op_sel_hi:[1,0]
	ds_read2_b64 v[36:39], v187 offset0:164 offset1:166
	s_waitcnt lgkmcnt(3)
	v_mfma_f32_32x32x16_bf16 v[96:111], v[40:43], v[24:27], v[96:111]
	v_pk_mul_f32 v[88:89], v[88:89], v[14:15] op_sel_hi:[1,0]
	v_pk_mul_f32 v[90:91], v[90:91], v[14:15] op_sel_hi:[1,0]
	ds_read2_b64 v[40:43], v187 offset0:168 offset1:170
	s_waitcnt lgkmcnt(3)
	v_mfma_f32_32x32x16_bf16 v[96:111], v[44:47], v[28:31], v[96:111]
	v_pk_mul_f32 v[92:93], v[92:93], v[14:15] op_sel_hi:[1,0]
	v_pk_mul_f32 v[94:95], v[94:95], v[14:15] op_sel_hi:[1,0]
	ds_read2_b64 v[44:47], v187 offset0:172 offset1:174
	s_waitcnt lgkmcnt(3)
	v_mfma_f32_32x32x16_bf16 v[80:95], v[32:35], v[16:19], v[80:95]
	v_pk_mul_f32 v[64:65], v[64:65], v[14:15] op_sel_hi:[1,0]
	v_pk_mul_f32 v[66:67], v[66:67], v[14:15] op_sel_hi:[1,0]
	ds_read2_b64 v[32:35], v188 offset0:192 offset1:194
	s_waitcnt lgkmcnt(3)
	v_mfma_f32_32x32x16_bf16 v[80:95], v[36:39], v[20:23], v[80:95]
	v_pk_mul_f32 v[68:69], v[68:69], v[14:15] op_sel_hi:[1,0]
	v_pk_mul_f32 v[70:71], v[70:71], v[14:15] op_sel_hi:[1,0]
	ds_read2_b64 v[36:39], v188 offset0:196 offset1:198
	s_waitcnt lgkmcnt(3)
	v_mfma_f32_32x32x16_bf16 v[80:95], v[40:43], v[24:27], v[80:95]
	v_pk_mul_f32 v[72:73], v[72:73], v[14:15] op_sel_hi:[1,0]
	v_pk_mul_f32 v[74:75], v[74:75], v[14:15] op_sel_hi:[1,0]
	ds_read2_b64 v[40:43], v188 offset0:200 offset1:202
	s_waitcnt lgkmcnt(3)
	v_mfma_f32_32x32x16_bf16 v[80:95], v[44:47], v[28:31], v[80:95]
	v_pk_mul_f32 v[76:77], v[76:77], v[14:15] op_sel_hi:[1,0]
	v_pk_mul_f32 v[78:79], v[78:79], v[14:15] op_sel_hi:[1,0]
	ds_read2_b64 v[44:47], v188 offset0:204 offset1:206
	s_waitcnt lgkmcnt(3)
	v_mfma_f32_32x32x16_bf16 v[64:79], v[32:35], v[16:19], v[64:79]
	v_pk_mul_f32 v[48:49], v[48:49], v[14:15] op_sel_hi:[1,0]
	v_pk_mul_f32 v[50:51], v[50:51], v[14:15] op_sel_hi:[1,0]
	ds_read2_b64 v[32:35], v189 offset0:224 offset1:226
	s_waitcnt lgkmcnt(3)
	v_mfma_f32_32x32x16_bf16 v[64:79], v[36:39], v[20:23], v[64:79]
	v_pk_mul_f32 v[52:53], v[52:53], v[14:15] op_sel_hi:[1,0]
	v_pk_mul_f32 v[54:55], v[54:55], v[14:15] op_sel_hi:[1,0]
	ds_read2_b64 v[36:39], v189 offset0:228 offset1:230
	s_waitcnt lgkmcnt(3)
	v_mfma_f32_32x32x16_bf16 v[64:79], v[40:43], v[24:27], v[64:79]
	v_pk_mul_f32 v[56:57], v[56:57], v[14:15] op_sel_hi:[1,0]
	v_pk_mul_f32 v[58:59], v[58:59], v[14:15] op_sel_hi:[1,0]
	ds_read2_b64 v[40:43], v189 offset0:232 offset1:234
	s_waitcnt lgkmcnt(3)
	v_mfma_f32_32x32x16_bf16 v[64:79], v[44:47], v[28:31], v[64:79]
	v_pk_mul_f32 v[60:61], v[60:61], v[14:15] op_sel_hi:[1,0]
	v_pk_mul_f32 v[62:63], v[62:63], v[14:15] op_sel_hi:[1,0]
	ds_read2_b64 v[44:47], v189 offset0:236 offset1:238
	s_waitcnt lgkmcnt(3)
	v_mfma_f32_32x32x16_bf16 v[48:63], v[32:35], v[16:19], v[48:63]
	s_waitcnt lgkmcnt(2)
	v_mfma_f32_32x32x16_bf16 v[48:63], v[36:39], v[20:23], v[48:63]
	s_waitcnt lgkmcnt(1)
	v_mfma_f32_32x32x16_bf16 v[48:63], v[40:43], v[24:27], v[48:63]
	s_waitcnt lgkmcnt(0)
	v_mfma_f32_32x32x16_bf16 v[48:63], v[44:47], v[28:31], v[48:63]
	s_branch .Lm2_h2done2
.Lm2_lazy2:
	v_mov_b32_e32 v1, v249
	v_fma_f32 v16, v16, s50, -v1
	v_exp_f32_e32 v16, v16
	v_fma_f32 v17, v17, s50, -v1
	v_exp_f32_e32 v17, v17
	v_fma_f32 v18, v18, s50, -v1
	v_exp_f32_e32 v18, v18
	v_fma_f32 v19, v19, s50, -v1
	v_exp_f32_e32 v19, v19
	v_fma_f32 v20, v20, s50, -v1
	v_exp_f32_e32 v20, v20
	v_fma_f32 v21, v21, s50, -v1
	v_exp_f32_e32 v21, v21
	v_fma_f32 v22, v22, s50, -v1
	v_exp_f32_e32 v22, v22
	v_fma_f32 v23, v23, s50, -v1
	v_exp_f32_e32 v23, v23
	v_fma_f32 v24, v24, s50, -v1
	v_exp_f32_e32 v24, v24
	v_fma_f32 v25, v25, s50, -v1
	v_exp_f32_e32 v25, v25
	v_fma_f32 v26, v26, s50, -v1
	v_exp_f32_e32 v26, v26
	v_fma_f32 v27, v27, s50, -v1
	v_exp_f32_e32 v27, v27
	v_fma_f32 v28, v28, s50, -v1
	v_exp_f32_e32 v28, v28
	v_fma_f32 v29, v29, s50, -v1
	v_exp_f32_e32 v29, v29
	v_fma_f32 v30, v30, s50, -v1
	v_exp_f32_e32 v30, v30
	v_fma_f32 v31, v31, s50, -v1
	v_exp_f32_e32 v31, v31
	v_fma_f32 v32, v32, s50, -v1
	v_exp_f32_e32 v32, v32
	v_fma_f32 v33, v33, s50, -v1
	v_exp_f32_e32 v33, v33
	v_fma_f32 v34, v34, s50, -v1
	v_exp_f32_e32 v34, v34
	v_fma_f32 v35, v35, s50, -v1
	v_exp_f32_e32 v35, v35
	v_fma_f32 v36, v36, s50, -v1
	v_exp_f32_e32 v36, v36
	v_fma_f32 v37, v37, s50, -v1
	v_exp_f32_e32 v37, v37
	v_fma_f32 v38, v38, s50, -v1
	v_exp_f32_e32 v38, v38
	v_fma_f32 v39, v39, s50, -v1
	v_exp_f32_e32 v39, v39
	v_fma_f32 v40, v40, s50, -v1
	v_exp_f32_e32 v40, v40
	v_fma_f32 v41, v41, s50, -v1
	v_exp_f32_e32 v41, v41
	v_fma_f32 v42, v42, s50, -v1
	v_exp_f32_e32 v42, v42
	v_fma_f32 v43, v43, s50, -v1
	v_exp_f32_e32 v43, v43
	v_fma_f32 v44, v44, s50, -v1
	v_exp_f32_e32 v44, v44
	v_fma_f32 v45, v45, s50, -v1
	v_exp_f32_e32 v45, v45
	v_fma_f32 v46, v46, s50, -v1
	v_exp_f32_e32 v46, v46
	v_fma_f32 v47, v47, s50, -v1
	v_exp_f32_e32 v47, v47
	v_add_f32_e32 v1, v16, v17
	v_add_f32_e32 v15, v24, v25
	v_add_f32_e32 v238, v32, v33
	v_add_f32_e32 v186, v40, v41
	v_add_f32_e32 v1, v18, v1
	v_add_f32_e32 v15, v26, v15
	v_add_f32_e32 v238, v34, v238
	v_add_f32_e32 v186, v42, v186
	v_add_f32_e32 v1, v19, v1
	v_add_f32_e32 v15, v27, v15
	v_add_f32_e32 v238, v35, v238
	v_add_f32_e32 v186, v43, v186
	v_add_f32_e32 v1, v20, v1
	v_add_f32_e32 v15, v28, v15
	v_add_f32_e32 v238, v36, v238
	v_add_f32_e32 v186, v44, v186
	v_add_f32_e32 v1, v21, v1
	v_add_f32_e32 v15, v29, v15
	v_add_f32_e32 v238, v37, v238
	v_add_f32_e32 v186, v45, v186
	v_add_f32_e32 v1, v22, v1
	v_add_f32_e32 v15, v30, v15
	v_add_f32_e32 v238, v38, v238
	v_add_f32_e32 v186, v46, v186
	v_add_f32_e32 v1, v23, v1
	v_add_f32_e32 v15, v31, v15
	v_add_f32_e32 v238, v39, v238
	v_add_f32_e32 v186, v47, v186
	v_add_f32_e32 v1, v1, v15
	v_add_f32_e32 v238, v238, v186
	v_add_f32_e32 v1, v1, v238
	v_add_f32_e32 v225, v225, v1
	v_add3_u32 v186, s25, v168, v169
	v_add_u32_e32 v187, 0x7000, v186
	v_add_u32_e32 v188, 0x8000, v186
	v_add_u32_e32 v189, 0x9000, v186
	v_add_u32_e32 v186, 0x6000, v186
	v_cvt_pk_bf16_f32 v16, v16, v17
	v_cvt_pk_bf16_f32 v17, v18, v19
	v_cvt_pk_bf16_f32 v18, v20, v21
	v_cvt_pk_bf16_f32 v19, v22, v23
	v_cvt_pk_bf16_f32 v20, v24, v25
	v_cvt_pk_bf16_f32 v21, v26, v27
	v_cvt_pk_bf16_f32 v22, v28, v29
	v_cvt_pk_bf16_f32 v23, v30, v31
	v_cvt_pk_bf16_f32 v24, v32, v33
	v_cvt_pk_bf16_f32 v25, v34, v35
	v_cvt_pk_bf16_f32 v26, v36, v37
	v_cvt_pk_bf16_f32 v27, v38, v39
	v_cvt_pk_bf16_f32 v28, v40, v41
	v_cvt_pk_bf16_f32 v29, v42, v43
	v_cvt_pk_bf16_f32 v30, v44, v45
	v_cvt_pk_bf16_f32 v31, v46, v47
	ds_read2_b64 v[32:35], v186 offset0:128 offset1:130
	ds_read2_b64 v[36:39], v186 offset0:132 offset1:134
	ds_read2_b64 v[40:43], v186 offset0:136 offset1:138
	ds_read2_b64 v[44:47], v186 offset0:140 offset1:142
	s_waitcnt lgkmcnt(3)
	v_mfma_f32_32x32x16_bf16 v[96:111], v[32:35], v[16:19], v[96:111]
	ds_read2_b64 v[32:35], v187 offset0:160 offset1:162
	s_waitcnt lgkmcnt(3)
	v_mfma_f32_32x32x16_bf16 v[96:111], v[36:39], v[20:23], v[96:111]
	ds_read2_b64 v[36:39], v187 offset0:164 offset1:166
	s_waitcnt lgkmcnt(3)
	v_mfma_f32_32x32x16_bf16 v[96:111], v[40:43], v[24:27], v[96:111]
	ds_read2_b64 v[40:43], v187 offset0:168 offset1:170
	s_waitcnt lgkmcnt(3)
	v_mfma_f32_32x32x16_bf16 v[96:111], v[44:47], v[28:31], v[96:111]
	ds_read2_b64 v[44:47], v187 offset0:172 offset1:174
	s_waitcnt lgkmcnt(3)
	v_mfma_f32_32x32x16_bf16 v[80:95], v[32:35], v[16:19], v[80:95]
	ds_read2_b64 v[32:35], v188 offset0:192 offset1:194
	s_waitcnt lgkmcnt(3)
	v_mfma_f32_32x32x16_bf16 v[80:95], v[36:39], v[20:23], v[80:95]
	ds_read2_b64 v[36:39], v188 offset0:196 offset1:198
	s_waitcnt lgkmcnt(3)
	v_mfma_f32_32x32x16_bf16 v[80:95], v[40:43], v[24:27], v[80:95]
	ds_read2_b64 v[40:43], v188 offset0:200 offset1:202
	s_waitcnt lgkmcnt(3)
	v_mfma_f32_32x32x16_bf16 v[80:95], v[44:47], v[28:31], v[80:95]
	ds_read2_b64 v[44:47], v188 offset0:204 offset1:206
	s_waitcnt lgkmcnt(3)
	v_mfma_f32_32x32x16_bf16 v[64:79], v[32:35], v[16:19], v[64:79]
	ds_read2_b64 v[32:35], v189 offset0:224 offset1:226
	s_waitcnt lgkmcnt(3)
	v_mfma_f32_32x32x16_bf16 v[64:79], v[36:39], v[20:23], v[64:79]
	ds_read2_b64 v[36:39], v189 offset0:228 offset1:230
	s_waitcnt lgkmcnt(3)
	v_mfma_f32_32x32x16_bf16 v[64:79], v[40:43], v[24:27], v[64:79]
	ds_read2_b64 v[40:43], v189 offset0:232 offset1:234
	s_waitcnt lgkmcnt(3)
	v_mfma_f32_32x32x16_bf16 v[64:79], v[44:47], v[28:31], v[64:79]
	ds_read2_b64 v[44:47], v189 offset0:236 offset1:238
	s_waitcnt lgkmcnt(3)
	v_mfma_f32_32x32x16_bf16 v[48:63], v[32:35], v[16:19], v[48:63]
	s_waitcnt lgkmcnt(2)
	v_mfma_f32_32x32x16_bf16 v[48:63], v[36:39], v[20:23], v[48:63]
	s_waitcnt lgkmcnt(1)
	v_mfma_f32_32x32x16_bf16 v[48:63], v[40:43], v[24:27], v[48:63]
	s_waitcnt lgkmcnt(0)
	v_mfma_f32_32x32x16_bf16 v[48:63], v[44:47], v[28:31], v[48:63]
.Lm2_h2done2:
	s_cmp_eq_u32 s19, 0
	s_cbranch_scc1 .Lm2_A_nowrite
	s_add_i32 s2, s24, 0xa800
	s_cmp_eq_u32 s2, 0x1f800
	s_cselect_b32 s2, 0, s2
	s_add_i32 s2, s2, 16
	v_add3_u32 v1, s2, v171, v191
	s_waitcnt vmcnt(4)
	ds_write_b128 v1, v[2:5]
	s_waitcnt vmcnt(3)
	ds_write_b128 v1, v[6:9] offset:12800
	v_add3_u32 v1, s2, v241, v242
	s_waitcnt vmcnt(2)
	ds_write_b128 v1, v[10:13] offset:256
	v_add3_u32 v1, s2, v243, v242
	v_add_u32_e32 v2, 0x6400, v1
	v_add_u32_e32 v1, 0x8600, v1
	s_waitcnt vmcnt(1)
	ds_write2_b64 v2, v[160:161], v[162:163] offset1:1
	s_waitcnt vmcnt(0)
	ds_write2_b64 v1, v[164:165], v[166:167] offset1:1
.Lm2_A_nowrite:
	s_add_i32 s24, s24, 0xa800
	s_cmp_eq_u32 s24, 0x1f800
	s_cselect_b32 s24, 0, s24
	s_add_i32 s19, s19, 64
	s_mov_b64 s[4:5], 0x2000
	v_lshl_add_u64 v[230:231], v[230:231], 0, s[92:93]
	v_lshl_add_u64 v[228:229], v[228:229], 0, s[4:5]
	v_lshl_add_u64 v[226:227], v[226:227], 0, s[38:39]
	s_add_i32 s2, s24, 16
	s_cmp_eq_u32 s3, s19
	s_cbranch_scc0 .Lm2_A_top
	s_branch .LBB0_437

.Lm2_tail_nobar:
	s_cbranch_scc1 .LBB0_439
	v_add3_u32 v1, s2, v244, v170
	ds_read_b128 v[2:5], v1
	s_waitcnt lgkmcnt(0)
	v_mfma_f32_32x32x16_bf16 v[16:31], v[2:5], v[148:151], 0
	ds_read_b128 v[2:5], v1 offset:12800
	s_waitcnt lgkmcnt(0)
	v_mfma_f32_32x32x16_bf16 v[32:47], v[2:5], v[148:151], 0
	ds_read_b128 v[2:5], v1 offset:32
	s_waitcnt lgkmcnt(0)
	v_mfma_f32_32x32x16_bf16 v[16:31], v[2:5], v[144:147], v[16:31]
	ds_read_b128 v[2:5], v1 offset:12832
	s_waitcnt lgkmcnt(0)
	v_mfma_f32_32x32x16_bf16 v[32:47], v[2:5], v[144:147], v[32:47]
	ds_read_b128 v[2:5], v1 offset:64
	s_waitcnt lgkmcnt(0)
	v_mfma_f32_32x32x16_bf16 v[16:31], v[2:5], v[140:143], v[16:31]
	ds_read_b128 v[2:5], v1 offset:12864
	s_waitcnt lgkmcnt(0)
	v_mfma_f32_32x32x16_bf16 v[32:47], v[2:5], v[140:143], v[32:47]
	ds_read_b128 v[2:5], v1 offset:96
	s_waitcnt lgkmcnt(0)
	v_mfma_f32_32x32x16_bf16 v[16:31], v[2:5], v[132:135], v[16:31]
	ds_read_b128 v[2:5], v1 offset:12896
	s_waitcnt lgkmcnt(0)
	v_mfma_f32_32x32x16_bf16 v[32:47], v[2:5], v[132:135], v[32:47]
	ds_read_b128 v[2:5], v1 offset:128
	s_waitcnt lgkmcnt(0)
	v_mfma_f32_32x32x16_bf16 v[16:31], v[2:5], v[124:127], v[16:31]
	ds_read_b128 v[2:5], v1 offset:12928
	s_waitcnt lgkmcnt(0)
	v_mfma_f32_32x32x16_bf16 v[32:47], v[2:5], v[124:127], v[32:47]
	ds_read_b128 v[2:5], v1 offset:160
	s_waitcnt lgkmcnt(0)
	v_mfma_f32_32x32x16_bf16 v[16:31], v[2:5], v[120:123], v[16:31]
	ds_read_b128 v[2:5], v1 offset:12960
	s_waitcnt lgkmcnt(0)
	v_mfma_f32_32x32x16_bf16 v[32:47], v[2:5], v[120:123], v[32:47]
	ds_read_b128 v[2:5], v1 offset:192
	s_waitcnt lgkmcnt(0)
	v_mfma_f32_32x32x16_bf16 v[16:31], v[2:5], v[116:119], v[16:31]
	ds_read_b128 v[2:5], v1 offset:12992
	s_waitcnt lgkmcnt(0)
	v_mfma_f32_32x32x16_bf16 v[32:47], v[2:5], v[116:119], v[32:47]
	ds_read_b128 v[2:5], v1 offset:224
	s_waitcnt lgkmcnt(0)
	v_mfma_f32_32x32x16_bf16 v[16:31], v[2:5], v[112:115], v[16:31]
	ds_read_b128 v[2:5], v1 offset:13024
	s_waitcnt lgkmcnt(0)
	v_mfma_f32_32x32x16_bf16 v[32:47], v[2:5], v[112:115], v[32:47]
	ds_read_b128 v[2:5], v1 offset:256
	s_waitcnt lgkmcnt(0)
	v_mfma_f32_32x32x16_bf16 v[16:31], v[2:5], v[136:139], v[16:31]
	ds_read_b128 v[2:5], v1 offset:13056
	s_waitcnt lgkmcnt(0)
	v_mfma_f32_32x32x16_bf16 v[32:47], v[2:5], v[136:139], v[32:47]
	ds_read_b128 v[2:5], v1 offset:288
	s_waitcnt lgkmcnt(0)
	v_mfma_f32_32x32x16_bf16 v[16:31], v[2:5], v[156:159], v[16:31]
	ds_read_b128 v[2:5], v1 offset:13088
	s_waitcnt lgkmcnt(0)
	v_mfma_f32_32x32x16_bf16 v[32:47], v[2:5], v[156:159], v[32:47]
	ds_read_b128 v[2:5], v1 offset:320
	s_waitcnt lgkmcnt(0)
	v_mfma_f32_32x32x16_bf16 v[16:31], v[2:5], v[128:131], v[16:31]
	ds_read_b128 v[2:5], v1 offset:13120
	s_waitcnt lgkmcnt(0)
	v_mfma_f32_32x32x16_bf16 v[32:47], v[2:5], v[128:131], v[32:47]
	ds_read_b128 v[2:5], v1 offset:352
	s_waitcnt lgkmcnt(0)
	v_mfma_f32_32x32x16_bf16 v[16:31], v[2:5], v[152:155], v[16:31]
	ds_read_b128 v[2:5], v1 offset:13152
	s_waitcnt lgkmcnt(0)
	v_mfma_f32_32x32x16_bf16 v[32:47], v[2:5], v[152:155], v[32:47]
